# P0 input LayerNorm: the four wave sums by DPP + permlane swaps instead of ds_bpermute chains (on top of the f32 matrix-core folds)
# speedup vs baseline: 1.0137x; 1.0045x over previous
.LBB0_81:
	s_mov_b64 s[4:5], s[0:1]
	s_load_dwordx2 s[4:5], s[4:5], 0x0
	s_mov_b64 s[6:7], s[0:1]
	s_add_i32 s16, s14, 0xffe00000
	s_load_dwordx2 s[6:7], s[6:7], 0x0
	s_lshl_b64 s[34:35], s[16:17], 2
	s_waitcnt lgkmcnt(0)
	s_add_u32 s4, s4, s34
	s_mov_b32 s15, s17
	s_addc_u32 s5, s5, s35
	s_lshl_b64 s[34:35], s[14:15], 2
	v_lshl_add_u64 v[34:35], s[4:5], 0, v[66:67]
	s_add_u32 s4, s6, s34
	global_load_dwordx4 v[62:65], v[34:35], off
	global_load_dwordx4 v[58:61], v[34:35], off offset:1024
	global_load_dwordx4 v[50:53], v[34:35], off offset:2048
	global_load_dwordx4 v[54:57], v[34:35], off offset:3072
	s_addc_u32 s5, s7, s35
	v_lshl_add_u64 v[70:71], s[4:5], 0, v[66:67]
	global_load_dwordx4 v[46:49], v[70:71], off
	global_load_dwordx4 v[42:45], v[70:71], off offset:1024
	global_load_dwordx4 v[38:41], v[70:71], off offset:2048
	global_load_dwordx4 v[34:37], v[70:71], off offset:3072
	s_mov_b64 s[36:37], s[0:1]
	s_load_dwordx2 s[4:5], s[36:37], 0x80
	s_lshl_b64 s[34:35], s[16:17], 1
	s_mov_b64 s[18:19], s[0:1]
	s_mov_b64 s[20:21], s[0:1]
	s_mov_b64 s[22:23], s[0:1]
	s_waitcnt lgkmcnt(0)
	s_add_u32 s4, s4, s34
	s_addc_u32 s5, s5, s35
	v_lshl_add_u64 v[70:71], s[4:5], 0, v[68:69]
	v_add_co_u32_e32 v70, vcc, s39, v70
	s_lshl_b64 s[36:37], s[14:15], 1
	s_nop 0
	v_addc_co_u32_e32 v71, vcc, 0, v71, vcc
	s_mov_b64 s[24:25], s[0:1]
	s_mov_b64 s[26:27], s[0:1]
	s_mov_b64 s[28:29], s[0:1]
	s_mov_b64 s[30:31], s[0:1]
	s_waitcnt vmcnt(7)
	v_mov_b32_e32 v74, v63
	v_mov_b32_e32 v75, v64
	v_mov_b32_e32 v76, v62
	v_mov_b32_e32 v77, v65
	s_waitcnt vmcnt(6)
	v_mov_b32_e32 v78, v59
	v_mov_b32_e32 v79, v60
	v_mov_b32_e32 v80, v58
	v_mov_b32_e32 v81, v61
	s_waitcnt vmcnt(5)
	v_add_f32_e32 v82, v50, v51
	v_add_f32_e32 v84, v52, v53
	s_waitcnt vmcnt(4)
	v_mov_b32_e32 v83, v56
	v_mov_b32_e32 v85, v57
	v_pk_add_f32 v[74:75], v[74:75], v[76:77]
	v_pk_add_f32 v[76:77], v[78:79], v[80:81]
	v_pk_add_f32 v[78:79], v[82:83], v[84:85]
	v_add_f32_e32 v86, v74, v75
	s_waitcnt vmcnt(3)
	v_mov_b32_e32 v74, v47
	v_mov_b32_e32 v75, v48
	v_mov_b32_e32 v80, v46
	v_mov_b32_e32 v81, v49
	v_pk_add_f32 v[76:77], v[76:77], v[76:77] op_sel:[0,1] op_sel_hi:[1,0]
	s_waitcnt vmcnt(2)
	v_mov_b32_e32 v82, v43
	v_mov_b32_e32 v83, v44
	v_mov_b32_e32 v84, v42
	v_mov_b32_e32 v85, v45
	v_mov_b32_e32 v87, v54
	v_add_f32_e32 v86, 0, v86
	v_pk_add_f32 v[74:75], v[74:75], v[80:81]
	v_pk_add_f32 v[80:81], v[82:83], v[84:85]
	v_mov_b32_e32 v77, v55
	v_add_f32_e32 v84, v74, v75
	v_pk_add_f32 v[74:75], v[80:81], v[80:81] op_sel:[0,1] op_sel_hi:[1,0]
	v_pk_add_f32 v[76:77], v[86:87], v[76:77]
	s_waitcnt vmcnt(1)
	v_add_f32_e32 v88, v38, v39
	v_add_f32_e32 v90, v40, v41
	s_waitcnt vmcnt(0)
	v_mov_b32_e32 v93, v34
	v_mov_b32_e32 v89, v36
	v_mov_b32_e32 v91, v37
	v_add_f32_e32 v92, 0, v84
	v_pk_add_f32 v[76:77], v[76:77], v[78:79]
	v_mov_b32_e32 v75, v35
	v_pk_add_f32 v[82:83], v[88:89], v[90:91]
	v_add_f32_e32 v76, v76, v77
	v_pk_add_f32 v[74:75], v[92:93], v[74:75]
	v_pk_add_f32 v[74:75], v[74:75], v[82:83]
	s_nop 0
	v_add_f32_e32 v74, v74, v75
	s_nop 1
	v_add_f32_dpp v76, v76, v76 quad_perm:[1,0,3,2] row_mask:0xf bank_mask:0xf
	v_add_f32_dpp v74, v74, v74 quad_perm:[1,0,3,2] row_mask:0xf bank_mask:0xf
	s_nop 1
	v_add_f32_dpp v76, v76, v76 quad_perm:[2,3,0,1] row_mask:0xf bank_mask:0xf
	v_add_f32_dpp v74, v74, v74 quad_perm:[2,3,0,1] row_mask:0xf bank_mask:0xf
	s_nop 1
	v_add_f32_dpp v76, v76, v76 row_ror:4 row_mask:0xf bank_mask:0xf
	v_add_f32_dpp v74, v74, v74 row_ror:4 row_mask:0xf bank_mask:0xf
	s_nop 1
	v_add_f32_dpp v76, v76, v76 row_ror:8 row_mask:0xf bank_mask:0xf
	v_add_f32_dpp v74, v74, v74 row_ror:8 row_mask:0xf bank_mask:0xf
	s_nop 1
	v_mov_b32_e32 v77, v76
	v_mov_b32_e32 v75, v74
	s_nop 1
	v_permlane16_swap_b32_e32 v77, v76
	v_permlane16_swap_b32_e32 v75, v74
	s_nop 1
	v_add_f32_e32 v76, v77, v76
	v_add_f32_e32 v74, v75, v74
	v_mov_b32_e32 v77, v76
	v_mov_b32_e32 v75, v74
	s_nop 1
	v_permlane32_swap_b32_e32 v77, v76
	v_permlane32_swap_b32_e32 v75, v74
	s_nop 1
	v_add_f32_e32 v76, v77, v76
	v_add_f32_e32 v74, v75, v74
	v_fmamk_f32 v63, v76, 0xba800000, v63
	v_fmamk_f32 v62, v76, 0xba800000, v62
	v_fmamk_f32 v65, v76, 0xba800000, v65
	v_fmac_f32_e32 v64, 0xba800000, v76
	v_fmamk_f32 v59, v76, 0xba800000, v59
	v_fmamk_f32 v58, v76, 0xba800000, v58
	v_fmamk_f32 v61, v76, 0xba800000, v61
	v_fmac_f32_e32 v60, 0xba800000, v76
	v_fmamk_f32 v51, v76, 0xba800000, v51
	v_fmamk_f32 v50, v76, 0xba800000, v50
	v_fmamk_f32 v53, v76, 0xba800000, v53
	v_fmac_f32_e32 v52, 0xba800000, v76
	v_fmamk_f32 v57, v76, 0xba800000, v57
	v_fmamk_f32 v56, v76, 0xba800000, v56
	v_fmamk_f32 v55, v76, 0xba800000, v55
	v_fmac_f32_e32 v54, 0xba800000, v76
	v_mov_b32_e32 v83, v74
	v_pk_mul_f32 v[74:75], v[64:65], v[64:65]
	v_pk_mul_f32 v[76:77], v[62:63], v[62:63]
	v_pk_mul_f32 v[78:79], v[60:61], v[60:61]
	v_pk_mul_f32 v[80:81], v[58:59], v[58:59]
	v_pk_mov_b32 v[86:87], v[76:77], v[74:75] op_sel:[1,0]
	v_mov_b32_e32 v77, v75
	v_pk_mov_b32 v[74:75], v[80:81], v[78:79] op_sel:[1,0]
	v_mov_b32_e32 v81, v79
	v_mul_f32_e32 v82, v51, v51
	v_mul_f32_e32 v84, v53, v53
	v_fmamk_f32 v47, v83, 0xba800000, v47
	v_fmamk_f32 v46, v83, 0xba800000, v46
	v_fmamk_f32 v49, v83, 0xba800000, v49
	v_fmac_f32_e32 v48, 0xba800000, v83
	v_fmamk_f32 v43, v83, 0xba800000, v43
	v_fmamk_f32 v42, v83, 0xba800000, v42
	v_fmamk_f32 v45, v83, 0xba800000, v45
	v_fmac_f32_e32 v44, 0xba800000, v83
	v_pk_add_f32 v[76:77], v[86:87], v[76:77]
	v_pk_add_f32 v[74:75], v[74:75], v[80:81]
	v_mul_f32_e32 v91, v54, v54
	v_mul_f32_e32 v93, v55, v55
	v_mul_f32_e32 v90, v56, v56
	v_mul_f32_e32 v92, v57, v57
	v_fmamk_f32 v39, v83, 0xba800000, v39
	v_fmamk_f32 v38, v83, 0xba800000, v38
	v_fmamk_f32 v41, v83, 0xba800000, v41
	v_fmac_f32_e32 v40, 0xba800000, v83
	v_fmamk_f32 v37, v83, 0xba800000, v37
	v_fmamk_f32 v36, v83, 0xba800000, v36
	v_fmamk_f32 v35, v83, 0xba800000, v35
	v_fmac_f32_e32 v34, 0xba800000, v83
	v_pk_fma_f32 v[78:79], v[50:51], v[50:51], v[82:83] op_sel_hi:[1,1,0]
	v_pk_fma_f32 v[82:83], v[52:53], v[52:53], v[84:85] op_sel_hi:[1,1,0]
	v_pk_mul_f32 v[84:85], v[48:49], v[48:49]
	v_pk_mul_f32 v[86:87], v[46:47], v[46:47]
	v_pk_mul_f32 v[80:81], v[44:45], v[44:45]
	v_pk_mul_f32 v[88:89], v[42:43], v[42:43]
	v_pk_add_f32 v[76:77], v[76:77], v[76:77] op_sel:[0,1] op_sel_hi:[1,0]
	v_pk_add_f32 v[74:75], v[74:75], v[74:75] op_sel:[0,1] op_sel_hi:[1,0]
	v_mov_b32_e32 v79, v90
	v_mov_b32_e32 v83, v92
	v_pk_mov_b32 v[94:95], v[86:87], v[84:85] op_sel:[1,0]
	v_mov_b32_e32 v87, v85
	v_pk_mov_b32 v[84:85], v[88:89], v[80:81] op_sel:[1,0]
	v_mov_b32_e32 v89, v81
	v_mov_b32_e32 v77, v91
	v_mov_b32_e32 v75, v93
	v_mul_f32_e32 v90, v39, v39
	v_mul_f32_e32 v92, v41, v41
	v_pk_add_f32 v[78:79], v[78:79], v[82:83]
	v_pk_add_f32 v[86:87], v[94:95], v[86:87]
	v_pk_add_f32 v[84:85], v[84:85], v[88:89]
	v_pk_add_f32 v[74:75], v[76:77], v[74:75]
	v_mul_f32_e32 v96, v34, v34
	v_mul_f32_e32 v97, v35, v35
	v_mul_f32_e32 v98, v36, v36
	v_mul_f32_e32 v99, v37, v37
	v_pk_fma_f32 v[80:81], v[38:39], v[38:39], v[90:91] op_sel_hi:[1,1,0]
	v_pk_fma_f32 v[82:83], v[40:41], v[40:41], v[92:93] op_sel_hi:[1,1,0]
	v_pk_add_f32 v[76:77], v[86:87], v[86:87] op_sel:[0,1] op_sel_hi:[1,0]
	v_pk_add_f32 v[84:85], v[84:85], v[84:85] op_sel:[0,1] op_sel_hi:[1,0]
	v_pk_add_f32 v[74:75], v[74:75], v[78:79]
	v_mov_b32_e32 v81, v98
	v_mov_b32_e32 v83, v99
	v_mov_b32_e32 v77, v96
	v_mov_b32_e32 v85, v97
	v_add_f32_e32 v78, v74, v75
	v_pk_add_f32 v[80:81], v[80:81], v[82:83]
	v_pk_add_f32 v[74:75], v[76:77], v[84:85]
	v_pk_add_f32 v[74:75], v[74:75], v[80:81]
	v_mov_b32_e32 v76, v78
	s_nop 0
	v_add_f32_e32 v74, v74, v75
	s_nop 1
	v_add_f32_dpp v76, v76, v76 quad_perm:[1,0,3,2] row_mask:0xf bank_mask:0xf
	v_add_f32_dpp v74, v74, v74 quad_perm:[1,0,3,2] row_mask:0xf bank_mask:0xf
	s_nop 1
	v_add_f32_dpp v76, v76, v76 quad_perm:[2,3,0,1] row_mask:0xf bank_mask:0xf
	v_add_f32_dpp v74, v74, v74 quad_perm:[2,3,0,1] row_mask:0xf bank_mask:0xf
	s_nop 1
	v_add_f32_dpp v76, v76, v76 row_ror:4 row_mask:0xf bank_mask:0xf
	v_add_f32_dpp v74, v74, v74 row_ror:4 row_mask:0xf bank_mask:0xf
	s_nop 1
	v_add_f32_dpp v76, v76, v76 row_ror:8 row_mask:0xf bank_mask:0xf
	v_add_f32_dpp v74, v74, v74 row_ror:8 row_mask:0xf bank_mask:0xf
	s_nop 1
	v_mov_b32_e32 v77, v76
	v_mov_b32_e32 v75, v74
	s_nop 1
	v_permlane16_swap_b32_e32 v77, v76
	v_permlane16_swap_b32_e32 v75, v74
	s_nop 1
	v_add_f32_e32 v76, v77, v76
	v_add_f32_e32 v74, v75, v74
	v_mov_b32_e32 v77, v76
	v_mov_b32_e32 v75, v74
	s_nop 1
	v_permlane32_swap_b32_e32 v77, v76
	v_permlane32_swap_b32_e32 v75, v74
	s_nop 1
	v_add_f32_e32 v76, v77, v76
	v_add_f32_e32 v74, v75, v74
	v_fmamk_f32 v76, v76, 0x3a800000, v72
	v_mul_f32_e32 v77, 0x4f800000, v76
	v_cmp_gt_f32_e32 vcc, s33, v76
	v_fmamk_f32 v74, v74, 0x3a800000, v72
	v_cndmask_b32_e32 v75, v76, v77, vcc
	v_sqrt_f32_e32 v76, v75
	v_mul_f32_e32 v77, 0x4f800000, v74
	v_cmp_gt_f32_e64 s[4:5], s33, v74
	v_add_u32_e32 v78, -1, v76
	s_nop 0
	v_cndmask_b32_e64 v74, v74, v77, s[4:5]
	v_sqrt_f32_e32 v77, v74
	v_add_u32_e32 v79, 1, v76
	v_fma_f32 v80, -v78, v76, v75
	v_fma_f32 v81, -v79, v76, v75
	v_cmp_ge_f32_e64 s[6:7], 0, v80
	v_add_u32_e32 v80, 1, v77
	s_nop 0
	v_cndmask_b32_e64 v76, v76, v78, s[6:7]
	v_add_u32_e32 v78, -1, v77
	v_cmp_lt_f32_e64 s[6:7], 0, v81
	v_fma_f32 v81, -v80, v77, v74
	s_nop 0
	v_cndmask_b32_e64 v76, v76, v79, s[6:7]
	v_fma_f32 v79, -v78, v77, v74
	v_cmp_ge_f32_e64 s[6:7], 0, v79
	v_mul_f32_e32 v82, 0x37800000, v76
	v_cndmask_b32_e32 v76, v76, v82, vcc
	v_cndmask_b32_e64 v77, v77, v78, s[6:7]
	v_cmp_lt_f32_e64 s[6:7], 0, v81
	v_cmp_class_f32_e32 vcc, v75, v73
	s_nop 0
	v_cndmask_b32_e64 v77, v77, v80, s[6:7]
	v_cndmask_b32_e32 v75, v76, v75, vcc
	v_mul_f32_e32 v76, 0x37800000, v77
	v_div_scale_f32 v78, s[6:7], v75, v75, 1.0
	v_cndmask_b32_e64 v76, v77, v76, s[4:5]
	v_cmp_class_f32_e64 s[4:5], v74, v73
	v_rcp_f32_e32 v77, v78
	v_div_scale_f32 v79, vcc, 1.0, v75, 1.0
	v_cndmask_b32_e64 v76, v76, v74, s[4:5]
	v_div_scale_f32 v80, s[4:5], v76, v76, 1.0
	v_rcp_f32_e32 v82, v80
	v_fma_f32 v74, -v78, v77, 1.0
	v_fmac_f32_e32 v77, v74, v77
	v_mul_f32_e32 v74, v79, v77
	v_fma_f32 v83, -v80, v82, 1.0
	v_div_scale_f32 v81, s[4:5], 1.0, v76, 1.0
	v_fma_f32 v84, -v78, v74, v79
	v_fmac_f32_e32 v82, v83, v82
	v_fmac_f32_e32 v74, v84, v77
	v_mul_f32_e32 v83, v81, v82
	v_fma_f32 v78, -v78, v74, v79
	v_fma_f32 v79, -v80, v83, v81
	v_div_fmas_f32 v74, v78, v77, v74
	v_fmac_f32_e32 v83, v79, v82
	v_div_fixup_f32 v74, v74, v75, 1.0
	v_fma_f32 v75, -v80, v83, v81
	s_mov_b64 vcc, s[4:5]
	v_div_fmas_f32 v75, v75, v82, v83
	v_pk_mul_f32 v[62:63], v[74:75], v[62:63] op_sel_hi:[0,1]
	v_pk_mul_f32 v[64:65], v[74:75], v[64:65] op_sel_hi:[0,1]
	v_pk_mul_f32 v[58:59], v[74:75], v[58:59] op_sel_hi:[0,1]
	v_pk_mul_f32 v[60:61], v[74:75], v[60:61] op_sel_hi:[0,1]
	v_pk_mul_f32 v[50:51], v[74:75], v[50:51] op_sel_hi:[0,1]
	v_pk_mul_f32 v[52:53], v[74:75], v[52:53] op_sel_hi:[0,1]
	v_pk_mul_f32 v[54:55], v[74:75], v[54:55] op_sel_hi:[0,1]
	v_pk_mul_f32 v[56:57], v[74:75], v[56:57] op_sel_hi:[0,1]
	v_div_fixup_f32 v74, v75, v76, 1.0
	v_pk_fma_f32 v[64:65], v[4:5], v[64:65], v[8:9]
	v_pk_fma_f32 v[62:63], v[2:3], v[62:63], v[6:7]
	v_pk_fma_f32 v[52:53], v[20:21], v[52:53], v[24:25]
	v_pk_fma_f32 v[50:51], v[18:19], v[50:51], v[22:23]
	v_pk_fma_f32 v[56:57], v[28:29], v[56:57], v[32:33]
	v_pk_fma_f32 v[54:55], v[26:27], v[54:55], v[30:31]
	v_pk_mul_f32 v[46:47], v[74:75], v[46:47] op_sel_hi:[0,1]
	v_pk_mul_f32 v[48:49], v[74:75], v[48:49] op_sel_hi:[0,1]
	v_bfe_u32 v75, v62, 16, 1
	v_bfe_u32 v77, v64, 16, 1
	v_pk_fma_f32 v[60:61], v[12:13], v[60:61], v[16:17]
	v_bfe_u32 v76, v63, 16, 1
	v_bfe_u32 v78, v65, 16, 1
	v_pk_mul_f32 v[42:43], v[74:75], v[42:43] op_sel_hi:[0,1]
	v_pk_mul_f32 v[44:45], v[74:75], v[44:45] op_sel_hi:[0,1]
	v_pk_mul_f32 v[38:39], v[74:75], v[38:39] op_sel_hi:[0,1]
	v_pk_mul_f32 v[40:41], v[74:75], v[40:41] op_sel_hi:[0,1]
	v_bfe_u32 v83, v50, 16, 1
	v_bfe_u32 v84, v51, 16, 1
	v_bfe_u32 v85, v52, 16, 1
	v_bfe_u32 v86, v53, 16, 1
	v_pk_mul_f32 v[34:35], v[74:75], v[34:35] op_sel_hi:[0,1]
	v_pk_mul_f32 v[36:37], v[74:75], v[36:37] op_sel_hi:[0,1]
	v_bfe_u32 v74, v54, 16, 1
	v_bfe_u32 v87, v55, 16, 1
	v_bfe_u32 v88, v56, 16, 1
	v_bfe_u32 v89, v57, 16, 1
	v_add3_u32 v62, v62, v75, s12
	v_add3_u32 v64, v64, v77, s12
	v_bfe_u32 v82, v61, 16, 1
	v_add3_u32 v63, v63, v76, s12
	v_add3_u32 v65, v65, v78, s12
	v_add3_u32 v50, v50, v83, s12
	v_add3_u32 v75, v51, v84, s12
	v_add3_u32 v51, v52, v85, s12
	v_add3_u32 v52, v53, v86, s12
	v_add3_u32 v53, v54, v74, s12
	v_add3_u32 v54, v55, v87, s12
	v_add3_u32 v55, v56, v88, s12
	v_add3_u32 v56, v57, v89, s12
	v_lshrrev_b32_e32 v57, 16, v62
	v_lshrrev_b32_e32 v62, 16, v64
	v_add3_u32 v61, v61, v82, s12
	v_lshrrev_b32_e32 v82, 16, v50
	v_lshrrev_b32_e32 v83, 16, v51
	v_and_or_b32 v50, v63, s38, v57
	v_and_or_b32 v51, v65, s38, v62
	global_store_dwordx2 v[70:71], v[50:51], off
	s_load_dwordx2 s[4:5], s[18:19], 0x80
	v_pk_fma_f32 v[58:59], v[10:11], v[58:59], v[14:15]
	v_pk_fma_f32 v[48:49], v[4:5], v[48:49], v[8:9]
	v_bfe_u32 v79, v58, 16, 1
	v_bfe_u32 v80, v59, 16, 1
	v_pk_fma_f32 v[46:47], v[2:3], v[46:47], v[6:7]
	v_pk_fma_f32 v[42:43], v[10:11], v[42:43], v[14:15]
	v_add3_u32 v58, v58, v79, s12
	v_bfe_u32 v81, v60, 16, 1
	v_add3_u32 v59, v59, v80, s12
	v_pk_fma_f32 v[38:39], v[18:19], v[38:39], v[22:23]
	v_pk_fma_f32 v[36:37], v[28:29], v[36:37], v[32:33]
	v_pk_fma_f32 v[34:35], v[26:27], v[34:35], v[30:31]
	v_bfe_u32 v64, v46, 16, 1
	v_bfe_u32 v76, v48, 16, 1
	v_lshrrev_b32_e32 v58, 16, v58
	v_bfe_u32 v78, v42, 16, 1
	v_add3_u32 v60, v60, v81, s12
	v_bfe_u32 v74, v47, 16, 1
	v_bfe_u32 v77, v49, 16, 1
	v_bfe_u32 v79, v43, 16, 1
	v_bfe_u32 v84, v38, 16, 1
	v_lshrrev_b32_e32 v53, 16, v53
	v_bfe_u32 v88, v34, 16, 1
	v_bfe_u32 v89, v35, 16, 1
	v_bfe_u32 v90, v36, 16, 1
	v_bfe_u32 v91, v37, 16, 1
	v_add3_u32 v57, v46, v64, s12
	v_add3_u32 v48, v48, v76, s12
	v_and_or_b32 v46, v59, s38, v58
	v_add3_u32 v58, v42, v78, s12
	s_waitcnt lgkmcnt(0)
	s_add_u32 s4, s4, s36
	v_lshrrev_b32_e32 v60, 16, v60
	v_bfe_u32 v85, v39, 16, 1
	v_lshrrev_b32_e32 v55, 16, v55
	v_add3_u32 v62, v47, v74, s12
	v_add3_u32 v49, v49, v77, s12
	v_add3_u32 v59, v43, v79, s12
	v_and_or_b32 v43, v52, s38, v83
	v_add3_u32 v52, v38, v84, s12
	v_and_or_b32 v38, v54, s38, v53
	v_add3_u32 v34, v34, v88, s12
	v_add3_u32 v53, v35, v89, s12
	v_add3_u32 v35, v36, v90, s12
	v_add3_u32 v54, v37, v91, s12
	v_lshrrev_b32_e32 v36, 16, v57
	v_lshrrev_b32_e32 v37, 16, v48
	v_lshrrev_b32_e32 v48, 16, v58
	s_addc_u32 s5, s5, s37
	v_and_or_b32 v47, v61, s38, v60
	v_add3_u32 v60, v39, v85, s12
	v_and_or_b32 v39, v56, s38, v55
	v_lshrrev_b32_e32 v50, 16, v52
	v_lshrrev_b32_e32 v52, 16, v34
	v_lshrrev_b32_e32 v55, 16, v35
	v_and_or_b32 v34, v62, s38, v36
	v_and_or_b32 v35, v49, s38, v37
	v_and_or_b32 v36, v59, s38, v48
	v_lshl_add_u64 v[48:49], s[4:5], 0, v[68:69]
	v_add_co_u32_e32 v48, vcc, s39, v48
	v_pk_fma_f32 v[44:45], v[12:13], v[44:45], v[16:17]
	s_nop 0
	v_addc_co_u32_e32 v49, vcc, 0, v49, vcc
	global_store_dwordx2 v[48:49], v[34:35], off
	s_load_dwordx2 s[4:5], s[20:21], 0x80
	v_bfe_u32 v80, v44, 16, 1
	v_bfe_u32 v81, v45, 16, 1
	v_add3_u32 v44, v44, v80, s12
	v_add3_u32 v45, v45, v81, s12
	s_waitcnt lgkmcnt(0)
	s_add_u32 s4, s4, s34
	s_addc_u32 s5, s5, s35
	v_lshl_add_u64 v[34:35], s[4:5], 0, v[68:69]
	v_add_co_u32_e32 v34, vcc, s39, v34
	v_lshrrev_b32_e32 v44, 16, v44
	s_nop 0
	v_addc_co_u32_e32 v35, vcc, 0, v35, vcc
	global_store_dwordx2 v[34:35], v[46:47], off offset:512
	s_load_dwordx2 s[4:5], s[22:23], 0x80
	v_and_or_b32 v37, v45, s38, v44
	v_and_or_b32 v42, v75, s38, v82
	v_pk_fma_f32 v[40:41], v[20:21], v[40:41], v[24:25]
	v_and_or_b32 v44, v53, s38, v52
	s_waitcnt lgkmcnt(0)
	s_add_u32 s4, s4, s36
	s_addc_u32 s5, s5, s37
	v_lshl_add_u64 v[34:35], s[4:5], 0, v[68:69]
	v_add_co_u32_e32 v34, vcc, s39, v34
	v_bfe_u32 v86, v40, 16, 1
	s_nop 0
	v_addc_co_u32_e32 v35, vcc, 0, v35, vcc
	global_store_dwordx2 v[34:35], v[36:37], off offset:512
	s_load_dwordx2 s[4:5], s[24:25], 0x80
	v_bfe_u32 v87, v41, 16, 1
	v_add3_u32 v40, v40, v86, s12
	v_add3_u32 v41, v41, v87, s12
	v_lshrrev_b32_e32 v51, 16, v40
	s_waitcnt lgkmcnt(0)
	s_add_u32 s4, s4, s34
	s_addc_u32 s5, s5, s35
	v_lshl_add_u64 v[34:35], s[4:5], 0, v[68:69]
	v_add_co_u32_e32 v34, vcc, s39, v34
	v_and_or_b32 v40, v60, s38, v50
	s_nop 0
	v_addc_co_u32_e32 v35, vcc, 0, v35, vcc
	global_store_dwordx2 v[34:35], v[42:43], off offset:1024
	s_load_dwordx2 s[4:5], s[26:27], 0x80
	v_and_or_b32 v41, v41, s38, v51
	v_and_or_b32 v45, v54, s38, v55
	s_waitcnt lgkmcnt(0)
	s_add_u32 s4, s4, s36
	s_addc_u32 s5, s5, s37
	v_lshl_add_u64 v[34:35], s[4:5], 0, v[68:69]
	v_add_co_u32_e32 v34, vcc, s39, v34
	s_nop 1
	v_addc_co_u32_e32 v35, vcc, 0, v35, vcc
	global_store_dwordx2 v[34:35], v[40:41], off offset:1024
	s_load_dwordx2 s[4:5], s[28:29], 0x80
	s_waitcnt lgkmcnt(0)
	s_add_u32 s4, s4, s34
	s_addc_u32 s5, s5, s35
	v_lshl_add_u64 v[34:35], s[4:5], 0, v[68:69]
	v_add_co_u32_e32 v34, vcc, s39, v34
	s_nop 1
	v_addc_co_u32_e32 v35, vcc, 0, v35, vcc
	global_store_dwordx2 v[34:35], v[38:39], off offset:1536
	s_load_dwordx2 s[4:5], s[30:31], 0x80
	s_waitcnt lgkmcnt(0)
	s_add_u32 s4, s4, s36
	s_addc_u32 s5, s5, s37
	v_lshl_add_u64 v[34:35], s[4:5], 0, v[68:69]
	s_addk_i32 s13, 0x1000
	s_add_i32 s14, s14, 0x400000
	v_add_co_u32_e32 v34, vcc, 0x7200000, v34
	s_cmpk_gt_u32 s13, 0x6fff
	s_nop 0
	v_addc_co_u32_e32 v35, vcc, 0, v35, vcc
	global_store_dwordx2 v[34:35], v[44:45], off offset:1536
	s_cbranch_scc0 .LBB0_81
